# RWKV LoRA stage rebalanced across wave halves (waves 4-7 take the a-LoRA MFMAs and sigmoid) on top of the addressing version
# baseline (speedup 1.0000x reference)
.LBB0_1204:
	s_waitcnt vmcnt(2)
	v_mov_b32_e32 v56, v174
	s_load_dwordx4 s[20:23], s[72:73], 0x120
	s_lshl_b32 s3, s2, 6
	v_ashrrev_i32_e32 v57, 6, v56
	v_lshlrev_b32_e32 v0, 4, v57
	v_bfe_u32 v22, v56, 4, 2
	s_and_b32 s5, s3, 0x3c0
	v_and_b32_e32 v63, 48, v0
	v_and_b32_e32 v62, 15, v56
	v_lshlrev_b32_e32 v2, 3, v22
	v_or_b32_e32 v23, s5, v63
	v_or_b32_e32 v0, v23, v62
	v_cmp_gt_i32_e64 s[18:19], 4, v57
	v_cmp_lt_i32_e64 s[6:7], 3, v57
	v_mov_b32_e32 v1, 0
	v_lshlrev_b32_e32 v76, 1, v2
	s_and_saveexec_b64 s[8:9], s[6:7]
	s_xor_b64 s[8:9], exec, s[8:9]
	s_cbranch_execz .LBB0_1206
	v_lshlrev_b32_e32 v0, 8, v0
	v_lshrrev_b32_e32 v212, 1, v0
	v_mov_b32_e32 v213, 0
	s_waitcnt lgkmcnt(0)
	v_lshl_add_u64 v[2:3], s[22:23], 0, v[0:1]
	v_mov_b32_e32 v77, v1
	v_lshl_add_u64 v[0:1], v[2:3], 0, v[76:77]
	s_mov_b64 s[10:11], 0x2540000
	v_lshl_add_u64 v[16:17], v[0:1], 0, s[10:11]
	s_mov_b64 s[10:11], 0x2540080
	v_lshl_add_u64 v[18:19], v[0:1], 0, s[10:11]
	s_mov_b64 s[10:11], 0x25400c0
	v_lshl_add_u64 v[20:21], v[0:1], 0, s[10:11]
	v_lshl_add_u64 v[212:213], s[22:23], 0, v[212:213]
	v_lshl_add_u64 v[212:213], v[212:213], 0, v[76:77]
	s_mov_b64 s[10:11], 0x2520000
	v_lshl_add_u64 v[212:213], v[212:213], 0, s[10:11]
	global_load_dwordx4 v[216:219], v[212:213], off
	global_load_dwordx4 v[220:223], v[212:213], off offset:64

.LBB0_1210:
	s_or_b64 exec, exec, s[12:13]
	s_lshl_b32 s3, s2, 7
	s_and_b32 s3, s3, 0xfffff800
	v_or_b32_e32 v88, s3, v62
	s_add_u32 s12, s22, 0xf700000
	v_ashrrev_i32_e32 v89, 31, v88
	s_addc_u32 s13, s23, 0
	v_lshlrev_b64 v[32:33], 9, v[88:89]
	v_lshl_add_u64 v[32:33], s[12:13], 0, v[32:33]
	v_lshl_add_u64 v[32:33], v[32:33], 0, v[76:77]
	v_mov_b64_e32 v[34:35], 0xc0
	v_mov_b64_e32 v[36:37], 0x80
	v_mov_b64_e32 v[38:39], 64
	v_mov_b64_e32 v[48:49], v[32:33]
	s_and_saveexec_b64 s[14:15], s[6:7]
	s_mov_b64 s[16:17], 0x100
	v_lshl_add_u64 v[48:49], v[32:33], 0, s[16:17]
	v_mov_b64_e32 v[34:35], 0x1c0
	v_mov_b64_e32 v[36:37], 0x180
	v_mov_b64_e32 v[38:39], 0x140
	s_or_b64 exec, exec, s[14:15]
	v_lshl_add_u64 v[50:51], v[32:33], 0, v[38:39]
	v_lshl_add_u64 v[52:53], v[32:33], 0, v[36:37]
	v_lshl_add_u64 v[54:55], v[32:33], 0, v[34:35]
	global_load_dwordx4 v[32:35], v[48:49], off
	global_load_dwordx4 v[224:227], v[48:49], off offset:-128
	global_load_dwordx4 v[228:231], v[48:49], off offset:-64
	global_load_dwordx4 v[36:39], v[50:51], off
	global_load_dwordx4 v[40:43], v[52:53], off
	global_load_dwordx4 v[44:47], v[54:55], off
	s_mov_b32 s4, 0x2aaaaaab
	v_mul_hi_i32 v48, v56, s4
	v_lshrrev_b32_e32 v49, 31, v48
	v_ashrrev_i32_e32 v48, 2, v48
	s_add_u32 s22, s22, 0x2800000
	v_add_u32_e32 v89, v48, v49
	s_movk_i32 s4, 0xffe8
	v_mov_b32_e32 v55, 0
	s_addc_u32 s23, s23, 0
	v_mad_u64_u32 v[58:59], s[14:15], v89, s4, v[56:57]
	v_mov_b32_e32 v54, v55
	v_mov_b32_e32 v53, v55
	v_mov_b32_e32 v52, v55
	v_mov_b32_e32 v51, v55
	v_mov_b32_e32 v50, v55
	v_mov_b32_e32 v49, v55
	v_mov_b32_e32 v48, v55
	s_and_saveexec_b64 s[14:15], s[10:11]
	s_cbranch_execz .LBB0_1228
	v_cmp_lt_i32_e32 vcc, 7, v58
	s_and_saveexec_b64 s[16:17], vcc
	s_xor_b64 s[16:17], exec, s[16:17]
	s_cbranch_execz .LBB0_1223
	v_cmp_lt_u32_e32 vcc, 15, v58
	s_and_saveexec_b64 s[24:25], vcc
	s_xor_b64 s[24:25], exec, s[24:25]
	s_cbranch_execz .LBB0_1220
	v_cmp_lt_u32_e32 vcc, 23, v58
	v_lshlrev_b32_e32 v48, 3, v58
	s_and_saveexec_b64 s[26:27], vcc
	s_xor_b64 s[26:27], exec, s[26:27]
	v_add_u32_e32 v60, 0x1540, v48
	s_andn2_saveexec_b64 s[26:27], s[26:27]
	v_add_u32_e32 v60, s29, v48
	s_or_b64 exec, exec, s[26:27]

.Lrw_noload:
	s_or_b64 exec, exec, s[22:23]
	s_and_saveexec_b64 s[22:23], s[6:7]
	s_xor_b64 s[22:23], exec, s[22:23]
	s_cbranch_execz .LBB0_1232
	v_mfma_f32_16x16x32_bf16 v[56:59], v[0:3], v[32:35], 0
	v_mfma_f32_16x16x32_bf16 v[56:59], v[4:7], v[36:39], v[56:59]
	v_mfma_f32_16x16x32_bf16 v[56:59], v[8:11], v[40:43], v[56:59]
	v_mfma_f32_16x16x32_bf16 v[56:59], v[12:15], v[44:47], v[56:59]
	v_mfma_f32_16x16x32_bf16 v[60:63], v[216:219], v[224:227], 0
	v_mfma_f32_16x16x32_bf16 v[60:63], v[220:223], v[228:231], v[60:63]
	v_add_u32_e32 v164, s100, v122
	s_nop 7
	ds_write_b128 v164, v[56:59] offset:37120
	s_nop 1
	v_add_f32_e32 v60, v20, v60
	v_add_f32_e32 v61, v21, v61
	v_add_f32_e32 v62, v22, v62
	v_add_f32_e32 v63, v23, v63
	v_mul_f32_e32 v60, 0xbfb8aa3b, v60
	v_mul_f32_e32 v61, 0xbfb8aa3b, v61
	v_mul_f32_e32 v62, 0xbfb8aa3b, v62
	v_mul_f32_e32 v63, 0xbfb8aa3b, v63
	v_exp_f32_e32 v60, v60
	v_exp_f32_e32 v61, v61
	v_exp_f32_e32 v62, v62
	v_exp_f32_e32 v63, v63
	v_add_f32_e32 v60, 1.0, v60
	v_add_f32_e32 v61, 1.0, v61
	v_add_f32_e32 v62, 1.0, v62
	v_add_f32_e32 v63, 1.0, v63
	v_rcp_f32_e32 v60, v60
	v_rcp_f32_e32 v61, v61
	v_rcp_f32_e32 v62, v62
	v_rcp_f32_e32 v63, v63
	s_nop 0
	ds_write_b128 v122, v[60:63] offset:33024

.LBB0_1233:
	v_mfma_f32_16x16x32_bf16 v[56:59], v[0:3], v[32:35], 0
	v_mfma_f32_16x16x32_bf16 v[56:59], v[4:7], v[36:39], v[56:59]
	s_cmp_lg_u32 s100, 0
	s_cselect_b32 s97, 0x800, 0
	v_add_u32_e32 v168, s97, v109
	s_nop 7
	s_nop 1
	v_add_f32_e32 v56, v16, v56
	v_add_f32_e32 v57, v17, v57
	v_add_f32_e32 v58, v18, v58
	v_add_f32_e32 v59, v19, v59
	v_mul_f32_e32 v56, 0xbfb8aa3b, v56
	v_mul_f32_e32 v57, 0xbfb8aa3b, v57
	v_mul_f32_e32 v58, 0xbfb8aa3b, v58
	v_mul_f32_e32 v59, 0xbfb8aa3b, v59
	v_exp_f32_e32 v56, v56
	v_exp_f32_e32 v57, v57
	v_exp_f32_e32 v58, v58
	v_exp_f32_e32 v59, v59
	v_add_f32_e32 v56, 1.0, v56
	v_add_f32_e32 v57, 1.0, v57
	v_add_f32_e32 v58, 1.0, v58
	v_add_f32_e32 v59, 1.0, v59
	v_rcp_f32_e32 v56, v56
	v_rcp_f32_e32 v57, v57
	v_rcp_f32_e32 v58, v58
	v_rcp_f32_e32 v59, v59
	v_mul_f32_e32 v56, 0xbf1b4598, v56
	v_mul_f32_e32 v57, 0xbf1b4598, v57
	v_mul_f32_e32 v58, 0xbf1b4598, v58
	v_mul_f32_e32 v59, 0xbf1b4598, v59
	v_mul_f32_e32 v56, 0x3fb8aa3b, v56
	v_mul_f32_e32 v57, 0x3fb8aa3b, v57
	v_mul_f32_e32 v58, 0x3fb8aa3b, v58
	v_mul_f32_e32 v59, 0x3fb8aa3b, v59
	v_exp_f32_e32 v56, v56
	v_exp_f32_e32 v57, v57
	v_exp_f32_e32 v58, v58
	v_exp_f32_e32 v59, v59
	s_nop 0
	v_cvt_pk_f16_f32 v60, v56, v57
	v_cvt_pk_f16_f32 v61, v58, v59
	ds_write_b64 v168, v[60:61] offset:28928
.LBB0_1234:
	s_or_b64 exec, exec, s[22:23]
	s_waitcnt lgkmcnt(0)
	s_barrier
	s_andn2_b64 vcc, exec, s[18:19]
	s_cbranch_vccnz .LBB0_1236
	v_lshl_add_u32 v56, s30, 13, v170
	global_load_dwordx4 v[32:35], v56, s[90:91]
	global_load_dwordx4 v[224:227], v56, s[90:91] offset:-128
	global_load_dwordx4 v[228:231], v56, s[90:91] offset:-64
	global_load_dwordx4 v[36:39], v56, s[90:91] offset:64
	global_load_dwordx4 v[40:43], v56, s[90:91] offset:128
	global_load_dwordx4 v[44:47], v56, s[90:91] offset:192
